# S5 helper: hand-written 16-step complex scan (2 packed FMA + 1 packed cvt per step, forcing terms read up front) and packed GELU tail
# speedup vs baseline: 1.0035x; 1.0035x over previous
.LBB0_398:
	s_or_b64 exec, exec, s[38:39]
	v_lshl_or_b32 v2, s8, 10, v142
	v_mov_b32_e32 v3, v0
	v_lshl_add_u64 v[2:3], v[68:69], 0, v[2:3]
	global_load_ushort v212, v[2:3], off
	global_load_ushort v213, v[2:3], off offset:1024
	global_load_ushort v214, v[2:3], off offset:2048
	global_load_ushort v215, v[2:3], off offset:3072
	v_add_u32_e32 v91, v143, v102
	ds_read_b128 v[92:95], v91 offset:12544
	ds_read_b128 v[164:167], v91 offset:13056
	ds_read_b128 v[216:219], v91 offset:13568
	ds_read_b128 v[220:223], v146 offset:12544
	ds_read_b128 v[224:227], v91 offset:14592
	ds_read_b128 v[228:231], v91 offset:15104
	ds_read_b128 v[244:247], v91 offset:15616
	ds_read_b128 v[248:251], v147 offset:12544
	v_add_u32_e32 v96, 0xf000, v138
	v_add_u32_e32 v97, 0xf400, v138
	v_add_u32_e32 v159, 0xf800, v138
	s_andn2_b64 vcc, exec, s[50:51]
	s_waitcnt lgkmcnt(7)
	v_mfma_f32_16x16x32_bf16 v[92:95], v[12:15], v[92:95], 0
	s_waitcnt lgkmcnt(6)
	v_mfma_f32_16x16x32_bf16 v[164:167], v[12:15], v[164:167], 0
	s_waitcnt lgkmcnt(5)
	v_mfma_f32_16x16x32_bf16 v[216:219], v[12:15], v[216:219], 0
	s_waitcnt lgkmcnt(4)
	v_mfma_f32_16x16x32_bf16 v[220:223], v[12:15], v[220:223], 0
	s_waitcnt lgkmcnt(3)
	v_mfma_f32_16x16x32_bf16 v[224:227], v[12:15], v[224:227], 0
	s_waitcnt lgkmcnt(2)
	v_mfma_f32_16x16x32_bf16 v[228:231], v[12:15], v[228:231], 0
	s_waitcnt lgkmcnt(1)
	v_mfma_f32_16x16x32_bf16 v[244:247], v[12:15], v[244:247], 0
	s_waitcnt lgkmcnt(0)
	v_mfma_f32_16x16x32_bf16 v[248:251], v[12:15], v[248:251], 0
	ds_write2_b32 v96, v92, v164 offset0:192 offset1:208
	ds_write2_b32 v97, v93, v165 offset0:64 offset1:80
	ds_write2_b32 v97, v94, v166 offset0:192 offset1:208
	ds_write2_b32 v159, v95, v167 offset0:64 offset1:80
	ds_write2_b32 v96, v216, v220 offset0:224 offset1:240
	ds_write2_b32 v97, v217, v221 offset0:96 offset1:112
	ds_write2_b32 v97, v218, v222 offset0:224 offset1:240
	ds_write2_b32 v159, v219, v223 offset0:96 offset1:112
	ds_write2_b32 v97, v224, v228 offset1:16
	ds_write2_b32 v97, v225, v229 offset0:128 offset1:144
	ds_write2_b32 v159, v226, v230 offset1:16
	ds_write2_b32 v159, v227, v231 offset0:128 offset1:144
	ds_write2_b32 v97, v244, v248 offset0:32 offset1:48
	ds_write2_b32 v97, v245, v249 offset0:160 offset1:176
	ds_write2_b32 v159, v246, v250 offset0:32 offset1:48
	ds_write2_b32 v159, v247, v251 offset0:160 offset1:176
	s_waitcnt lgkmcnt(0)
	ds_read2st64_b32 v[216:217], v140 offset1:1
	ds_read2st64_b32 v[218:219], v140 offset0:2 offset1:3
	ds_read2st64_b32 v[220:221], v140 offset0:4 offset1:5
	ds_read2st64_b32 v[222:223], v140 offset0:6 offset1:7
	ds_read2st64_b32 v[224:225], v140 offset0:8 offset1:9
	ds_read2st64_b32 v[226:227], v140 offset0:10 offset1:11
	ds_read2st64_b32 v[228:229], v140 offset0:12 offset1:13
	ds_read2st64_b32 v[230:231], v140 offset0:14 offset1:15
	ds_read2st64_b32 v[244:245], v140 offset0:16 offset1:17
	ds_read2st64_b32 v[246:247], v140 offset0:18 offset1:19
	ds_read2st64_b32 v[248:249], v140 offset0:20 offset1:21
	ds_read2st64_b32 v[250:251], v140 offset0:22 offset1:23
	ds_read2st64_b32 v[92:93], v140 offset0:24 offset1:25
	ds_read2st64_b32 v[94:95], v140 offset0:26 offset1:27
	ds_read2st64_b32 v[164:165], v140 offset0:28 offset1:29
	ds_read2st64_b32 v[166:167], v140 offset0:30 offset1:31
	s_waitcnt lgkmcnt(15)
	v_pk_fma_f32 v[14:15], v[64:65], v[60:61], v[216:217] op_sel:[0,1,0] op_sel_hi:[0,0,1] neg_lo:[1,0,0]
	v_pk_fma_f32 v[60:61], v[56:57], v[60:61], v[14:15] op_sel_hi:[0,1,1]
	v_cvt_pk_bf16_f32 v12, v60, v61
	ds_write_b16 v141, v12 offset:8192
	ds_write_b16_d16_hi v141, v12 offset:8320
	s_waitcnt lgkmcnt(15)
	v_pk_fma_f32 v[14:15], v[64:65], v[60:61], v[218:219] op_sel:[0,1,0] op_sel_hi:[0,0,1] neg_lo:[1,0,0]
	v_pk_fma_f32 v[60:61], v[56:57], v[60:61], v[14:15] op_sel_hi:[0,1,1]
	v_cvt_pk_bf16_f32 v13, v60, v61
	ds_write_b16 v141, v13 offset:8464
	ds_write_b16_d16_hi v141, v13 offset:8592
	s_waitcnt lgkmcnt(15)
	v_pk_fma_f32 v[14:15], v[64:65], v[60:61], v[220:221] op_sel:[0,1,0] op_sel_hi:[0,0,1] neg_lo:[1,0,0]
	v_pk_fma_f32 v[60:61], v[56:57], v[60:61], v[14:15] op_sel_hi:[0,1,1]
	v_cvt_pk_bf16_f32 v12, v60, v61
	ds_write_b16 v141, v12 offset:8736
	ds_write_b16_d16_hi v141, v12 offset:8864
	s_waitcnt lgkmcnt(15)
	v_pk_fma_f32 v[14:15], v[64:65], v[60:61], v[222:223] op_sel:[0,1,0] op_sel_hi:[0,0,1] neg_lo:[1,0,0]
	v_pk_fma_f32 v[60:61], v[56:57], v[60:61], v[14:15] op_sel_hi:[0,1,1]
	v_cvt_pk_bf16_f32 v13, v60, v61
	ds_write_b16 v141, v13 offset:9008
	ds_write_b16_d16_hi v141, v13 offset:9136
	s_waitcnt lgkmcnt(15)
	v_pk_fma_f32 v[14:15], v[64:65], v[60:61], v[224:225] op_sel:[0,1,0] op_sel_hi:[0,0,1] neg_lo:[1,0,0]
	v_pk_fma_f32 v[60:61], v[56:57], v[60:61], v[14:15] op_sel_hi:[0,1,1]
	v_cvt_pk_bf16_f32 v12, v60, v61
	ds_write_b16 v141, v12 offset:9280
	ds_write_b16_d16_hi v141, v12 offset:9408
	s_waitcnt lgkmcnt(15)
	v_pk_fma_f32 v[14:15], v[64:65], v[60:61], v[226:227] op_sel:[0,1,0] op_sel_hi:[0,0,1] neg_lo:[1,0,0]
	v_pk_fma_f32 v[60:61], v[56:57], v[60:61], v[14:15] op_sel_hi:[0,1,1]
	v_cvt_pk_bf16_f32 v13, v60, v61
	ds_write_b16 v141, v13 offset:9552
	ds_write_b16_d16_hi v141, v13 offset:9680
	s_waitcnt lgkmcnt(15)
	v_pk_fma_f32 v[14:15], v[64:65], v[60:61], v[228:229] op_sel:[0,1,0] op_sel_hi:[0,0,1] neg_lo:[1,0,0]
	v_pk_fma_f32 v[60:61], v[56:57], v[60:61], v[14:15] op_sel_hi:[0,1,1]
	v_cvt_pk_bf16_f32 v12, v60, v61
	ds_write_b16 v141, v12 offset:9824
	ds_write_b16_d16_hi v141, v12 offset:9952
	s_waitcnt lgkmcnt(15)
	v_pk_fma_f32 v[14:15], v[64:65], v[60:61], v[230:231] op_sel:[0,1,0] op_sel_hi:[0,0,1] neg_lo:[1,0,0]
	v_pk_fma_f32 v[60:61], v[56:57], v[60:61], v[14:15] op_sel_hi:[0,1,1]
	v_cvt_pk_bf16_f32 v13, v60, v61
	ds_write_b16 v141, v13 offset:10096
	ds_write_b16_d16_hi v141, v13 offset:10224
	s_waitcnt lgkmcnt(15)
	v_pk_fma_f32 v[14:15], v[64:65], v[60:61], v[244:245] op_sel:[0,1,0] op_sel_hi:[0,0,1] neg_lo:[1,0,0]
	v_pk_fma_f32 v[60:61], v[56:57], v[60:61], v[14:15] op_sel_hi:[0,1,1]
	v_cvt_pk_bf16_f32 v12, v60, v61
	ds_write_b16 v141, v12 offset:10368
	ds_write_b16_d16_hi v141, v12 offset:10496
	s_waitcnt lgkmcnt(15)
	v_pk_fma_f32 v[14:15], v[64:65], v[60:61], v[246:247] op_sel:[0,1,0] op_sel_hi:[0,0,1] neg_lo:[1,0,0]
	v_pk_fma_f32 v[60:61], v[56:57], v[60:61], v[14:15] op_sel_hi:[0,1,1]
	v_cvt_pk_bf16_f32 v13, v60, v61
	ds_write_b16 v141, v13 offset:10640
	ds_write_b16_d16_hi v141, v13 offset:10768
	s_waitcnt lgkmcnt(15)
	v_pk_fma_f32 v[14:15], v[64:65], v[60:61], v[248:249] op_sel:[0,1,0] op_sel_hi:[0,0,1] neg_lo:[1,0,0]
	v_pk_fma_f32 v[60:61], v[56:57], v[60:61], v[14:15] op_sel_hi:[0,1,1]
	v_cvt_pk_bf16_f32 v12, v60, v61
	ds_write_b16 v141, v12 offset:10912
	ds_write_b16_d16_hi v141, v12 offset:11040
	s_waitcnt lgkmcnt(15)
	v_pk_fma_f32 v[14:15], v[64:65], v[60:61], v[250:251] op_sel:[0,1,0] op_sel_hi:[0,0,1] neg_lo:[1,0,0]
	v_pk_fma_f32 v[60:61], v[56:57], v[60:61], v[14:15] op_sel_hi:[0,1,1]
	v_cvt_pk_bf16_f32 v13, v60, v61
	ds_write_b16 v141, v13 offset:11184
	ds_write_b16_d16_hi v141, v13 offset:11312
	s_waitcnt lgkmcnt(15)
	v_pk_fma_f32 v[14:15], v[64:65], v[60:61], v[92:93] op_sel:[0,1,0] op_sel_hi:[0,0,1] neg_lo:[1,0,0]
	v_pk_fma_f32 v[60:61], v[56:57], v[60:61], v[14:15] op_sel_hi:[0,1,1]
	v_cvt_pk_bf16_f32 v12, v60, v61
	ds_write_b16 v141, v12 offset:11456
	ds_write_b16_d16_hi v141, v12 offset:11584
	s_waitcnt lgkmcnt(15)
	v_pk_fma_f32 v[14:15], v[64:65], v[60:61], v[94:95] op_sel:[0,1,0] op_sel_hi:[0,0,1] neg_lo:[1,0,0]
	v_pk_fma_f32 v[60:61], v[56:57], v[60:61], v[14:15] op_sel_hi:[0,1,1]
	v_cvt_pk_bf16_f32 v13, v60, v61
	ds_write_b16 v141, v13 offset:11728
	ds_write_b16_d16_hi v141, v13 offset:11856
	s_waitcnt lgkmcnt(15)
	v_pk_fma_f32 v[14:15], v[64:65], v[60:61], v[164:165] op_sel:[0,1,0] op_sel_hi:[0,0,1] neg_lo:[1,0,0]
	v_pk_fma_f32 v[60:61], v[56:57], v[60:61], v[14:15] op_sel_hi:[0,1,1]
	v_cvt_pk_bf16_f32 v12, v60, v61
	ds_write_b16 v141, v12 offset:12000
	ds_write_b16_d16_hi v141, v12 offset:12128
	s_waitcnt lgkmcnt(15)
	v_pk_fma_f32 v[14:15], v[64:65], v[60:61], v[166:167] op_sel:[0,1,0] op_sel_hi:[0,0,1] neg_lo:[1,0,0]
	v_pk_fma_f32 v[60:61], v[56:57], v[60:61], v[14:15] op_sel_hi:[0,1,1]
	v_cvt_pk_bf16_f32 v13, v60, v61
	ds_write_b16 v141, v13 offset:12272
	ds_write_b16_d16_hi v141, v13 offset:12400
	s_waitcnt lgkmcnt(0)
	ds_read_b128 v[12:15], v144 offset:8192
	ds_read_b128 v[92:95], v145 offset:16640
	ds_read_b128 v[216:219], v144 offset:8256
	ds_read_b128 v[220:223], v145 offset:16704
	ds_read_b128 v[224:227], v144 offset:8320
	ds_read_b128 v[228:231], v145 offset:16768
	ds_read_b128 v[244:247], v144 offset:8384
	ds_read_b128 v[248:251], v145 offset:16832
	s_waitcnt lgkmcnt(6)
	v_mfma_f32_16x16x32_bf16 v[12:15], v[12:15], v[92:95], 0
	s_waitcnt lgkmcnt(4)
	v_mfma_f32_16x16x32_bf16 v[12:15], v[216:219], v[220:223], v[12:15]
	s_waitcnt lgkmcnt(2)
	v_mfma_f32_16x16x32_bf16 v[12:15], v[224:227], v[228:231], v[12:15]
	s_waitcnt lgkmcnt(0)
	v_mfma_f32_16x16x32_bf16 v[12:15], v[244:247], v[248:251], v[12:15]
	s_nop 7
	s_waitcnt vmcnt(0)
	v_lshlrev_b32_e32 v88, 16, v212
	v_lshlrev_b32_e32 v89, 16, v213
	v_lshlrev_b32_e32 v90, 16, v214
	v_lshlrev_b32_e32 v91, 16, v215
	v_pk_fma_f32 v[12:13], v[148:149], v[88:89], v[12:13] op_sel_hi:[0,1,1]
	v_pk_fma_f32 v[14:15], v[148:149], v[90:91], v[14:15] op_sel_hi:[0,1,1]
	v_mov_b32_e32 v88, 0x3dd2d3e8
	v_mov_b32_e32 v90, 0x40135761
	v_pk_mul_f32 v[92:93], v[12:13], v[12:13]
	v_pk_mul_f32 v[94:95], v[14:15], v[14:15]
	v_pk_fma_f32 v[92:93], v[92:93], v[88:89], v[90:91] op_sel_hi:[1,0,0]
	v_pk_fma_f32 v[94:95], v[94:95], v[88:89], v[90:91] op_sel_hi:[1,0,0]
	v_pk_mul_f32 v[92:93], v[92:93], v[12:13]
	v_pk_mul_f32 v[94:95], v[94:95], v[14:15]
	v_mov_b32_e32 v88, 1.0
	v_exp_f32_e32 v92, v92
	v_exp_f32_e32 v93, v93
	v_exp_f32_e32 v94, v94
	v_exp_f32_e32 v95, v95
	s_nop 0
	v_pk_add_f32 v[92:93], v[92:93], v[88:89] op_sel_hi:[1,0]
	v_pk_add_f32 v[94:95], v[94:95], v[88:89] op_sel_hi:[1,0]
	v_rcp_f32_e32 v92, v92
	v_rcp_f32_e32 v93, v93
	v_rcp_f32_e32 v94, v94
	v_rcp_f32_e32 v95, v95
	s_nop 0
	v_pk_fma_f32 v[12:13], v[12:13], v[92:93], v[12:13] neg_lo:[1,0,0] neg_hi:[1,0,0]
	v_pk_fma_f32 v[14:15], v[14:15], v[94:95], v[14:15] neg_lo:[1,0,0] neg_hi:[1,0,0]
	v_cvt_pk_bf16_f32 v12, v12, v13
	v_cvt_pk_bf16_f32 v14, v14, v15
	global_store_short v[2:3], v12, off
	global_store_short_d16_hi v[2:3], v12, off offset:1024
	global_store_short v[2:3], v14, off offset:2048
	global_store_short_d16_hi v[2:3], v14, off offset:3072
	s_waitcnt lgkmcnt(0)
	v_lshlrev_b32_e32 v1, 2, v128
	s_cbranch_vccnz .LBB0_408
	s_waitcnt vmcnt(4)
	v_lshlrev_b32_e32 v16, 16, v176
	v_lshlrev_b32_e32 v30, 16, v177
	v_lshlrev_b32_e32 v32, 16, v178
	v_lshlrev_b32_e32 v36, 16, v179
	v_lshlrev_b32_e32 v17, 16, v180
	v_lshlrev_b32_e32 v26, 16, v181
	v_lshlrev_b32_e32 v27, 16, v182
	v_lshlrev_b32_e32 v28, 16, v183
	v_lshlrev_b32_e32 v29, 16, v184
	v_lshlrev_b32_e32 v31, 16, v185
	v_lshlrev_b32_e32 v33, 16, v186
	v_lshlrev_b32_e32 v37, 16, v187
	v_lshlrev_b32_e32 v34, 16, v188
	v_lshlrev_b32_e32 v35, 16, v189
	v_lshlrev_b32_e32 v38, 16, v190
	v_lshlrev_b32_e32 v39, 16, v195
	v_lshlrev_b32_e32 v40, 16, v197
	v_lshlrev_b32_e32 v43, 16, v198
	v_lshlrev_b32_e32 v42, 16, v199
	v_lshlrev_b32_e32 v45, 16, v200
	v_lshlrev_b32_e32 v44, 16, v201
	v_lshlrev_b32_e32 v46, 16, v203
	v_lshlrev_b32_e32 v49, 16, v204
	v_lshlrev_b32_e32 v48, 16, v205
	v_lshlrev_b32_e32 v41, 16, v196
	v_lshlrev_b32_e32 v47, 16, v202
	v_lshlrev_b32_e32 v51, 16, v206
	v_lshlrev_b32_e32 v50, 16, v207
	v_lshlrev_b32_e32 v53, 16, v191
	v_lshlrev_b32_e32 v52, 16, v193
	v_lshlrev_b32_e32 v55, 16, v192
	v_lshlrev_b32_e32 v54, 16, v194
	v_add_f32_e32 v88, v155, v35
	v_mul_f32_e32 v88, 0xbfb8aa3b, v88
	v_exp_f32_e32 v88, v88
	v_pk_add_f32 v[12:13], v[32:33], v[26:27] neg_lo:[0,1] neg_hi:[0,1]
	v_pk_add_f32 v[2:3], v[30:31], v[16:17] neg_lo:[0,1] neg_hi:[0,1]
	v_fma_f32 v13, v150, v13, v27
	v_add_f32_e32 v88, 1.0, v88
	v_rcp_f32_e32 v88, v88
	v_mul_f32_e32 v92, v157, v13
	v_fma_f32 v3, v149, v3, v17
	s_bitcmp1_b32 s3, 0
	v_mul_f32_e32 v89, 0xbf6002b1, v88
	v_cmp_gt_f32_e32 vcc, s85, v89
	s_cselect_b32 s8, 0x5000, 0
	v_mov_b32_e32 v94, v0
	v_cndmask_b32_e32 v89, 0, v239, vcc
	v_fmac_f32_e32 v89, 0xbf6002b1, v88
	v_exp_f32_e32 v88, v89
	v_cndmask_b32_e32 v89, 0, v236, vcc
	s_add_i32 s9, s8, 0
	s_mul_i32 s8, s3, 0xab
	v_ldexp_f32 v90, v88, v89
	v_add_f32_e32 v88, v154, v39
	v_mul_f32_e32 v88, 0xbfb8aa3b, v88
	v_exp_f32_e32 v88, v88
	v_mov_b32_e32 v89, v0
	s_bfe_u32 s8, s8, 0x70009
	s_mul_i32 s8, s8, 3
	v_add_f32_e32 v88, 1.0, v88
	v_rcp_f32_e32 v91, v88
	v_mul_f32_e32 v88, v92, v92
	s_sub_i32 s8, s3, s8
	s_and_b32 s8, s8, 0xff
	v_mov_b32_dpp v89, v88 quad_perm:[1,0,3,2] row_mask:0xf bank_mask:0xf
	v_fmac_f32_e32 v89, v92, v92
	s_mulk_i32 s8, 0x1100
	s_add_i32 s8, s8, 0
	v_add_f32_dpp v88, v89, v89 quad_perm:[2,3,0,1] row_mask:0xf bank_mask:0xf bound_ctrl:1
	v_pk_add_f32 v[14:15], v[36:37], v[28:29] neg_lo:[0,1] neg_hi:[0,1]
	s_nop 0
	v_add_f32_dpp v88, v88, v88 row_half_mirror row_mask:0xf bank_mask:0xf bound_ctrl:1
	v_fma_f32 v15, v151, v15, v29
	s_nop 0
	v_add_f32_dpp v88, v88, v88 row_mirror row_mask:0xf bank_mask:0xf bound_ctrl:1
	s_nop 0
	v_readlane_b32 s26, v88, 16
	v_readlane_b32 s27, v88, 48
	v_readlane_b32 s24, v88, 0
	v_readlane_b32 s25, v88, 32
	v_mov_b32_e32 v88, s26
	v_mov_b32_e32 v89, s27
	v_pk_add_f32 v[88:89], s[24:25], v[88:89]
	s_nop 0
	v_add_f32_e32 v88, v88, v89
	v_add_f32_e32 v88, 0x2b8cbccc, v88
	v_cmp_gt_f32_e32 vcc, s82, v88
	v_mul_f32_e32 v89, 0x4b800000, v88
	s_nop 0
	v_cndmask_b32_e32 v88, v88, v89, vcc
	v_rsq_f32_e32 v88, v88
	s_nop 0
	v_mul_f32_e32 v89, 0x45800000, v88
	v_cndmask_b32_e32 v88, v88, v89, vcc
	v_add_f32_e32 v89, -1.0, v91
	v_fma_f32 v89, v158, v89, 1.0
	v_mul_f32_e32 v13, v89, v13
	v_mul_f32_e32 v89, v13, v3
	v_mul_f32_e32 v93, v156, v89
	v_mul_f32_e64 v88, v92, -v88
	s_nop 0
	v_mov_b32_dpp v94, v93 quad_perm:[1,0,3,2] row_mask:0xf bank_mask:0xf
	v_fmac_f32_e32 v94, v156, v89
	s_nop 1
	v_add_f32_dpp v89, v94, v94 quad_perm:[2,3,0,1] row_mask:0xf bank_mask:0xf bound_ctrl:1
	s_nop 1
	v_add_f32_dpp v89, v89, v89 row_half_mirror row_mask:0xf bank_mask:0xf bound_ctrl:1
	s_nop 1
	v_add_f32_dpp v89, v89, v89 row_mirror row_mask:0xf bank_mask:0xf bound_ctrl:1
	s_nop 0
	v_readlane_b32 s38, v89, 0
	v_readlane_b32 s52, v89, 16
	v_readlane_b32 s39, v89, 32
	v_readlane_b32 s53, v89, 48
	v_add_u32_e32 v89, s9, v1
	ds_write2st64_b32 v89, v90, v88 offset1:16
	v_mul_f32_e64 v88, v91, -v88
	ds_write2st64_b32 v89, v88, v13 offset0:32 offset1:48
	ds_write_b32 v89, v3 offset:16384
	v_add_u32_e32 v3, s8, v1
	ds_write_b32 v3, v15 offset:40960
	s_and_saveexec_b64 s[50:51], s[44:45]
	s_cbranch_execz .LBB0_401
	s_lshl_b32 s24, s96, 2
	v_mov_b32_e32 v88, s52
	v_mov_b32_e32 v89, s53
	s_add_i32 s24, s8, s24
	v_pk_add_f32 v[88:89], s[38:39], v[88:89]
	v_mov_b32_e32 v13, s24
	v_add_f32_e32 v3, v88, v89
	ds_write_b32 v13, v3 offset:45056
